# additional small start stagger (blockIdx&63 x s_sleep 2) at the start of P2 so its K-loop/epilogue rounds drift apart across workgroups
# speedup vs baseline: 1.0121x; 1.0121x over previous
; #define LAS __attribute__((address_space(3)))
; __device__ __forceinline__ void mk_p2(const Ptrs& P, LAS unsigned char* lds, int tid, int wave, int lane, int bx, int G, bool dry) {
;     ...
;         for (int t = bx; t < 256; t += G) ctx_tile(P, lds, t, tid, wave, lane);
;         { pg8::Gemm g{H, WIN, MTOK, INW, DM}; pg8::StaticOrder S; S.init(MTOK, INW, G, bx);
;           EpiInF<false> E{Q, (bf16_t*)(ws + WS_K), (bf16_t*)(ws + WS_KC), P.qg, P.kg, rest, cv, (LAS float*)(lds + RING_BYTES)};
;           pg8::gemm_phase<EpiInF<false>, pg8::StaticOrder, true, true>(lds, g, S, E); }
.Lxok_done:
	s_or_b64 exec, exec, s[98:99]
	s_and_b32 s98, s97, 63
.Lstg2_loop:
	s_cmp_eq_u32 s98, 0
	s_cbranch_scc1 .Lstg2_done
	s_sleep 2
	s_sub_u32 s98, s98, 1
	s_branch .Lstg2_loop

; #define LAS __attribute__((address_space(3)))
; __device__ __forceinline__ bool attn_unit(const Ptrs& P, LAS unsigned char* lds, int unit, int tid, int wave, int lane, bool pre, int nxt) {
;     const int n = unit & 31, kh = (unit >> 5) & 3, b = unit >> 7;
;     const int g = wave & 3, q0 = 64 * (wave >> 2), h = kh * 4 + g, r = lane & 31, hh = lane >> 5;
;     unsigned char* ws = P.ws;
;     bf16_t* Qb = (bf16_t*)(ws + WS_Q) + (size_t)(b * SEQ + n * 128 + q0) * DM + h * 64;
;     const bf16_t* Kg = (const bf16_t*)(ws + WS_K) + (size_t)b * SEQ * KVW + kh * 64; const bf16_t* Vg = (const bf16_t*)(ws + WS_VT) + (size_t)(b * 4 + kh) * 64 * SEQ;
;     const bf16_t* Kcg = (const bf16_t*)(ws + WS_KC) + (size_t)b * CTX * KVW + kh * 64; const bf16_t* Vcg = (const bf16_t*)(ws + WS_VCT) + (size_t)(b * 4 + kh) * 64 * CTX;
;     float mq = fabsf(P.qg[lane]), mk = fabsf(P.kg[lane]);
; #pragma unroll
;     for (int o = 1; o < 64; o <<= 1) { mq = fmaxf(mq, __shfl_xor(mq, o)); mk = fmaxf(mk, __shfl_xor(mk, o)); }
;     const float sink2 = P.sink[h] * LOG2E; const float mshift = fmaxf(64.0f * QSCALE * mq * mk, sink2);
;     bf16x8_t qf[2][4];
; #pragma unroll
;     for (int cb = 0; cb < 2; ++cb)
; #pragma unroll
;         for (int ds = 0; ds < 4; ++ds) qf[cb][ds] = __builtin_nontemporal_load((const bf16x8_t*)(Qb + (size_t)(32 * cb + r) * DM + 16 * ds + 8 * hh));
;     f32x16 o[2][2];
; #pragma unroll
;     for (int db = 0; db < 2; ++db)
; #pragma unroll
;         for (int cb = 0; cb < 2; ++cb)
; #pragma unroll
;             for (int i = 0; i < 16; ++i) o[db][cb][i] = 0.f;
;     float rs[2] = {0.f, 0.f};
;     f32x16 negm;
; #pragma unroll
;     for (int i = 0; i < 16; ++i) negm[i] = -mshift;
; __device__ __forceinline__ void mk_p3(const Ptrs& P, LAS unsigned char* lds, int tid, int wave, int lane, int bx, int G, bool dry) {
;     ...
;         { bool pre = false; for (int u = bx; u < NB * 32 * 4; u += G) pre = attn_unit(P, lds, u, tid, wave, lane, pre, u + G < NB * 32 * 4 ? u + G : -1); }
.LBB9_305:
	s_cmp_lt_i32 s92, 4
	s_cselect_b64 s[2:3], -1, 0
	s_and_b64 s[22:23], s[2:3], s[0:1]
	s_andn2_b64 vcc, exec, s[22:23]
	s_cbranch_vccnz .LBB9_444
	v_writelane_b32 v251, s22, 33
	s_cmpk_gt_i32 s97, 0x1ff
	v_and_b32_e32 v171, 31, v208
	v_writelane_b32 v251, s23, 34
	v_writelane_b32 v251, s80, 35
	v_lshrrev_b32_e32 v184, 5, v170
	s_nop 0
	v_writelane_b32 v251, s81, 36
	v_writelane_b32 v251, s96, 37
	v_writelane_b32 v251, s83, 38
	v_writelane_b32 v251, s97, 39
	s_cbranch_scc1 .LBB9_413
	v_mbcnt_lo_u32_b32 v0, -1, 0
	v_mbcnt_hi_u32_b32 v0, -1, v0
	v_and_b32_e32 v1, 64, v0
	v_add_u32_e32 v1, 64, v1
	v_xor_b32_e32 v2, 1, v0
	v_cmp_lt_i32_e32 vcc, v2, v1
	s_bfe_u32 s0, s40, 0x20006
	v_writelane_b32 v251, s0, 40
	v_cndmask_b32_e32 v2, v0, v2, vcc
	v_lshlrev_b32_e32 v185, 2, v2
	v_xor_b32_e32 v2, 2, v0
	v_cmp_lt_i32_e32 vcc, v2, v1
	s_lshl_b32 s0, s50, 4
	s_and_b32 s33, s0, 0x3fffffc0
	v_cndmask_b32_e32 v2, v0, v2, vcc
	v_lshlrev_b32_e32 v186, 2, v2
	v_xor_b32_e32 v2, 4, v0
	v_cmp_lt_i32_e32 vcc, v2, v1
	s_cmpk_lt_u32 s40, 0x8c0
	s_cselect_b64 s[54:55], -1, 0
	v_cndmask_b32_e32 v2, v0, v2, vcc
	v_lshlrev_b32_e32 v187, 2, v2
	v_xor_b32_e32 v2, 8, v0
	v_cmp_lt_i32_e32 vcc, v2, v1
	s_or_b32 s2, s0, 63
	s_or_b32 s3, s33, 32
	v_cndmask_b32_e32 v2, v0, v2, vcc
	v_lshlrev_b32_e32 v188, 2, v2
	v_xor_b32_e32 v2, 16, v0
	v_cmp_lt_i32_e32 vcc, v2, v1
	v_or_b32_e32 v5, 32, v170
	v_lshlrev_b32_e32 v191, 4, v184
	v_cndmask_b32_e32 v2, v0, v2, vcc
	v_lshlrev_b32_e32 v189, 2, v2
	v_xor_b32_e32 v2, 32, v0
	v_cmp_lt_i32_e32 vcc, v2, v1
	v_mov_b32_e32 v1, 0
	v_mul_u32_u24_e32 v6, 0x110, v5
	v_cndmask_b32_e32 v0, v0, v2, vcc
	v_lshlrev_b32_e32 v190, 2, v0
	v_lshlrev_b32_e32 v0, 2, v184
	v_sub_u32_e32 v0, v171, v0
	v_cmp_lt_i32_e64 s[36:37], 10, v0
	v_cmp_gt_i32_e64 s[0:1], 1, v0
	v_cmp_gt_i32_e64 s[4:5], 2, v0
	v_writelane_b32 v251, s36, 41
	v_cmp_gt_i32_e64 s[6:7], 3, v0
	v_cmp_gt_i32_e64 s[8:9], 4, v0
	v_writelane_b32 v251, s37, 42
	v_cmp_lt_i32_e64 s[36:37], 15, v0
	v_cmp_gt_i32_e64 s[10:11], 9, v0
	v_cmp_gt_i32_e64 s[12:13], 10, v0
	v_writelane_b32 v251, s36, 43
	v_cmp_gt_i32_e64 s[14:15], 11, v0
	v_cmp_gt_i32_e64 s[16:17], 12, v0
	v_writelane_b32 v251, s37, 44
	v_cmp_lt_i32_e64 s[36:37], 16, v0
	v_cmp_gt_i32_e64 s[18:19], 17, v0
	v_cmp_gt_i32_e64 s[20:21], 18, v0
	v_writelane_b32 v251, s36, 45
	v_cmp_gt_i32_e64 s[22:23], 19, v0
	v_cmp_gt_i32_e64 s[24:25], 20, v0
	v_writelane_b32 v251, s37, 46
	v_cmp_lt_i32_e64 s[36:37], 17, v0
	v_cmp_gt_i32_e64 s[26:27], 25, v0
	v_cmp_gt_i32_e64 s[28:29], 26, v0
	v_writelane_b32 v251, s36, 47
	v_cmp_gt_i32_e64 s[30:31], 27, v0
	v_cmp_gt_i32_e64 s[34:35], 28, v0
	v_writelane_b32 v251, s37, 48
	v_cmp_lt_i32_e64 s[36:37], 18, v0
	v_cmp_lt_i32_e64 s[56:57], -1, v0
	v_cmp_lt_i32_e64 s[86:87], 0, v0
	v_writelane_b32 v251, s36, 49
	v_cmp_lt_i32_e64 s[60:61], 1, v0
	v_cmp_lt_i32_e64 s[62:63], 2, v0
	v_writelane_b32 v251, s37, 50
	v_cmp_lt_i32_e64 s[36:37], 23, v0
	v_cmp_lt_i32_e64 s[64:65], 7, v0
	v_cmp_lt_i32_e64 s[66:67], 8, v0
	v_writelane_b32 v251, s36, 51
	v_cmp_lt_i32_e64 s[72:73], 9, v0
	v_lshlrev_b32_e32 v4, 3, v184
	v_writelane_b32 v251, s37, 52
	v_cmp_lt_i32_e64 s[36:37], 24, v0
	v_mul_u32_u24_e32 v3, 0x110, v171
	v_lshlrev_b32_e32 v2, 10, v171
	v_writelane_b32 v251, s36, 53
	s_movk_i32 s52, 0x110
	v_add3_u32 v3, v3, v191, 0
	v_writelane_b32 v251, s37, 54
	v_cmp_lt_i32_e64 s[36:37], 25, v0
	v_lshlrev_b32_e32 v176, 1, v4
	s_mov_b32 s77, 0
	v_writelane_b32 v251, s36, 55
	v_add_u32_e32 v195, 0x4800, v3
	v_add_u32_e32 v198, 0xd400, v3
	v_writelane_b32 v251, s37, 56
	v_cmp_lt_i32_e64 s[36:37], 26, v0
	v_lshlrev_b32_e32 v0, 2, v170
	v_mad_u32_u24 v200, v5, s52, 0
	v_writelane_b32 v251, s36, 57
	v_mad_u32_u24 v201, v171, s52, 0
	s_mov_b64 s[68:69], 0
	v_writelane_b32 v251, s37, 58
	s_add_u32 s36, s90, 0x6200000
	v_writelane_b32 v251, s36, 59
	s_addc_u32 s36, s91, 0
	v_writelane_b32 v251, s36, 60
	s_add_u32 s36, s90, 0x7200000
	v_writelane_b32 v251, s36, 61
	s_addc_u32 s36, s91, 0
	v_writelane_b32 v251, s36, 62
	v_mov_b32_e32 v178, v176
	v_readlane_b32 s36, v251, 16
	s_add_u32 s36, s90, 0x4200000
	v_readlane_b32 s37, v251, 17
	v_readlane_b32 s38, v251, 18
	v_readlane_b32 s39, v251, 19
	v_readlane_b32 s40, v251, 20
	v_readlane_b32 s41, v251, 21
	v_readlane_b32 s42, v251, 22
	v_readlane_b32 s43, v251, 23
	v_readlane_b32 s44, v251, 24
	v_readlane_b32 s45, v251, 25
	v_readlane_b32 s46, v251, 26
	v_readlane_b32 s47, v251, 27
	v_readlane_b32 s48, v251, 28
	v_readlane_b32 s49, v251, 29
	v_readlane_b32 s50, v251, 30
	v_readlane_b32 s51, v251, 31
	v_writelane_b32 v251, s36, 63
	s_addc_u32 s36, s91, 0
	v_writelane_b32 v250, s36, 0
	s_add_u32 s36, s90, 0x6a00000
	v_writelane_b32 v250, s36, 1
	s_addc_u32 s36, s91, 0
	v_writelane_b32 v250, s36, 2
	s_add_u32 s36, s90, 0x7280000
	v_writelane_b32 v250, s36, 3
	s_addc_u32 s36, s91, 0
	v_writelane_b32 v250, s36, 4
	s_add_u32 s36, s90, 0x2000000
	v_writelane_b32 v250, s36, 5
	s_addc_u32 s36, s91, 0
	v_lshl_add_u64 v[172:173], s[40:41], 0, v[0:1]
	v_writelane_b32 v250, s36, 6
	s_add_i32 s40, 0, 0x11800
	s_add_i32 s76, 0, 0x16000
	v_writelane_b32 v250, s40, 7
	v_writelane_b32 v250, s76, 8
	v_writelane_b32 v250, s88, 9
	v_lshl_add_u64 v[174:175], s[42:43], 0, v[0:1]
	v_readlane_b32 s36, v251, 32
	v_writelane_b32 v250, s89, 10
	v_writelane_b32 v250, s90, 11
	v_writelane_b32 v250, s91, 12
	v_add3_u32 v0, v6, v191, 0
	v_mul_u32_u24_e32 v6, 0x90, v171
	v_writelane_b32 v250, s92, 13
	v_lshl_or_b32 v192, s36, 6, v170
	s_movk_i32 s37, 0x90
	v_add3_u32 v196, v6, v191, 0
	v_writelane_b32 v250, s93, 14
	v_add_u32_e32 v193, 0xfffffb80, v192
	v_add_u32_e32 v194, 0x4800, v0
	v_add_u32_e32 v197, 0xd400, v0
	v_add_u32_e32 v199, 0x8c00, v196
	v_mad_u32_u24 v202, v171, s37, 0
	v_mov_b32_e32 v179, v1
	v_lshlrev_b32_e32 v180, 1, v2
	v_mov_b32_e32 v181, v1
	s_mov_b32 s36, 0xf0f0f0f1
	s_movk_i32 s37, 0xffef
	s_movk_i32 s38, 0x490
	s_mov_b32 s39, 0x38e38e39
	v_readlane_b32 s42, v251, 39
	v_writelane_b32 v250, s94, 22
	v_writelane_b32 v250, s94, 23
	v_mov_b32_e32 v254, 0x24008
	ds_read_b32 v254, v254
	s_waitcnt lgkmcnt(0)
	v_readfirstlane_b32 s98, v254
	s_nop 3
	s_cmp_eq_u32 s98, 1
	s_cbranch_scc0 .Lrm_a
	s_cmpk_lg_i32 s94, 0x100
	s_cbranch_scc1 .Lrm_a
	s_and_b32 s98, s42, 7
	s_lshl_b32 s98, s98, 3
	s_bfe_u32 s99, s42, 0x30003
	s_or_b32 s98, s98, s99
	s_and_b32 vcc_lo, s98, 7
	s_lshl_b32 vcc_lo, vcc_lo, 3
	s_lshr_b32 vcc_hi, s98, 3
	s_or_b32 vcc_lo, vcc_lo, vcc_hi
	s_nop 0
